# attention phase: static priority raise given to waves 4-7 instead of waves 0-3
# speedup vs baseline: 1.0021x; 1.0021x over previous
.LBB0_106:
	s_andn2_b64 vcc, exec, s[8:9]
	s_cbranch_vccnz .LBB0_273
	v_readlane_b32 s2, v254, 36
	s_cmp_lt_i32 s2, 4
	s_cbranch_scc1 .LBB0_109
	s_setprio 1
